# one static s_setprio 1 for waves 0-3 at kernel entry (other half, on top of the early first LDS-DMA piece)
# baseline (speedup 1.0000x reference)
_Z11mega_kernel6Paramsii:
	s_load_dwordx2 s[34:35], s[0:1], 0x130
	s_load_dwordx4 s[76:79], s[0:1], 0x120
	s_load_dwordx8 s[24:31], s[0:1], 0x100
	s_load_dword s92, s[0:1], 0x148
	s_load_dwordx2 s[82:83], s[0:1], 0x140
	s_add_u32 s4, s0, 0x140
	s_addc_u32 s5, s1, 0
	v_and_b32_e32 v181, 0x3ff, v0
	s_nop 1
	v_readfirstlane_b32 s32, v181
	s_nop 3
	s_lshr_b32 s32, s32, 6
	s_cmp_lt_u32 s32, 4
	s_cbranch_scc0 .Lprio_half_done
	s_setprio 1
